# P4 half-block scan-first reorder guarded by grid==512 (otherwise same as previous best)
# speedup vs baseline: 1.0075x; 1.0075x over previous
.LBB0_449:
	s_or_b64 exec, exec, s[0:1]
	v_writelane_b32 v253, s76, 42
	s_cmpk_gt_i32 s55, 0x23f
	s_waitcnt lgkmcnt(0)
	v_writelane_b32 v253, s77, 43
	v_writelane_b32 v253, s78, 44
	v_writelane_b32 v253, s79, 45
	v_writelane_b32 v253, s80, 46
	v_writelane_b32 v253, s81, 47
	v_writelane_b32 v253, s82, 48
	v_writelane_b32 v253, s83, 49
	s_barrier
	s_cbranch_scc1 .LBB0_494
	s_bfe_u32 s98, s55, 0x10003
	s_cmp_eq_u32 s92, 0x200
	s_cselect_b32 s98, s98, 0
	s_cmp_eq_u32 s98, 1
	v_writelane_b32 v255, s98, 47
	s_cbranch_scc1 .LBB0_494
